# v114 + two of the six stage loads of the heavier K-loop load segment deferred into the same wave's compute segment (both GEMM loops), re-tested with a paired measure
# baseline (speedup 1.0000x reference)
; #define PG8_STAGE(bufoff, gbase, voff) do { _Pragma("unroll") for (int _i = 0; _i < 2; ++_i) \
;         __builtin_amdgcn_global_load_lds((const unsigned*)((const char*)(gbase) + (voff)[_i]), (PG8_LAS unsigned*)(lds + (bufoff) + ldsw + _i * 8192), 16, 0, 0); } while (0)
; #define PG8_LDA(dst, b, h) do { _Pragma("unroll") for (int m = 0; m < 4; ++m) _Pragma("unroll") for (int k = 0; k < 2; ++k) dst[m][k] = *(const PG8_LAS bf16x8*)(lds + PG8_SA(b, h) + aoff + m * 2048 + k * 1024); } while (0)
; #define PG8_LDB(dst, b, h) do { _Pragma("unroll") for (int n = 0; n < 2; ++n) _Pragma("unroll") for (int k = 0; k < 2; ++k) dst[n][k] = *(const PG8_LAS bf16x8*)(lds + PG8_SB(b, h) + boff + n * 2048 + k * 1024); } while (0)
; #define PG8_MMA(ai, bj, At, Bt) do { __builtin_amdgcn_s_setprio(1); _Pragma("unroll") for (int m = 0; m < 4; ++m) _Pragma("unroll") for (int n = 0; n < 2; ++n) _Pragma("unroll") for (int k = 0; k < 2; ++k) \
;         acc[ai][bj][m][n] = __builtin_amdgcn_mfma_f32_16x16x32_bf16(Bt[n][k], At[m][k], acc[ai][bj][m][n], 0, 0, 0); __builtin_amdgcn_s_setprio(0); } while (0)
; #define PG8_WAIT_V(n) asm volatile("s_waitcnt vmcnt(" #n ")" ::: "memory")
; #define PG8_WAIT_L(n) asm volatile("s_waitcnt lgkmcnt(" #n ")" ::: "memory")
; #define PG8_BAR __builtin_amdgcn_s_barrier()
; #define PG8_SCHED __builtin_amdgcn_sched_barrier(0)
; template <class Epi, class Sched, bool ALIGN_EPI = false, bool SP2 = false>
; __device__ __forceinline__ void gemm_phase(PG8_LAS unsigned char* lds, const Gemm g, const Sched& S, const Epi& E) {
;     ...
;             PG8_LDB(B0, 0, 0); PG8_LDB(B1, 0, 1); PG8_SCHED; PG8_LDA(At, 0, 0); PG8_STAGE(PG8_SA(1, 1), a1 + hstep, voffA);
;             PG8_WAIT_V(8); PG8_WAIT_L(0); PG8_BAR; PG8_MMA(0, 0, At, B0); PG8_MMA(0, 1, At, B1); PG8_BAR; PG8_SCHED;
;             PG8_LDA(At, 0, 1); PG8_STAGE(PG8_SB(0, 0), b2, voffB); PG8_STAGE(PG8_SB(0, 1), b2 + hstep, voffB); PG8_STAGE(PG8_SA(0, 0), a2, voffA);
;             PG8_WAIT_V(8); PG8_WAIT_L(0); PG8_BAR; PG8_MMA(1, 0, At, B0); PG8_MMA(1, 1, At, B1); PG8_BAR; PG8_SCHED;
.LBB0_274:
	s_add_u32 s22, s20, 0xfffc0080
	s_addc_u32 s23, s21, -1
	s_add_i32 s39, 0, 0x10000
	s_cmp_eq_u32 s38, 12
	s_cselect_b32 s25, s5, s23
	s_cselect_b32 s24, s13, s22
	v_add_u32_e32 v148, s39, v151
	s_cselect_b32 s23, s11, s37
	s_cselect_b32 s22, s35, s36
	s_add_i32 s45, 0, 0x14000
	ds_read_b128 v[140:143], v148
	ds_read_b128 v[144:147], v148 offset:1024
	ds_read_b128 v[156:159], v148 offset:2048
	ds_read_b128 v[160:163], v148 offset:3072
	v_add_u32_e32 v148, s45, v151
	ds_read_b128 v[164:167], v148
	ds_read_b128 v[168:171], v148 offset:1024
	ds_read_b128 v[182:185], v148 offset:2048
	ds_read_b128 v[186:189], v148 offset:3072
	v_lshl_add_u64 v[148:149], s[20:21], 0, v[136:137]
	s_add_i32 m0, s19, 0xc000
	ds_read_b128 v[190:193], v154
	ds_read_b128 v[194:197], v154 offset:1024
	ds_read_b128 v[198:201], v154 offset:2048
	ds_read_b128 v[202:205], v154 offset:3072
	ds_read_b128 v[228:231], v154 offset:4096
	ds_read_b128 v[236:239], v154 offset:5120
	ds_read_b128 v[240:243], v154 offset:6144
	ds_read_b128 v[244:247], v154 offset:7168
	global_load_lds_dwordx4 v[148:149], off
	v_lshl_add_u64 v[148:149], s[20:21], 0, v[138:139]
	s_add_i32 m0, s19, 0xe000
	s_nop 0
	global_load_lds_dwordx4 v[148:149], off
	s_waitcnt vmcnt(8)
	s_waitcnt lgkmcnt(0)
	s_barrier
	s_setprio 1
	s_waitcnt lgkmcnt(0)
	v_mfma_f32_16x16x32_bf16 v[124:127], v[140:143], v[190:193], v[124:127]
	v_mfma_f32_16x16x32_bf16 v[120:123], v[156:159], v[190:193], v[120:123]
	v_mfma_f32_16x16x32_bf16 v[108:111], v[140:143], v[198:201], v[108:111]
	v_mfma_f32_16x16x32_bf16 v[104:107], v[156:159], v[198:201], v[104:107]
	v_mfma_f32_16x16x32_bf16 v[92:95], v[140:143], v[228:231], v[92:95]
	v_mfma_f32_16x16x32_bf16 v[88:91], v[156:159], v[228:231], v[88:91]
	v_mfma_f32_16x16x32_bf16 v[76:79], v[140:143], v[240:243], v[76:79]
	v_mfma_f32_16x16x32_bf16 v[72:75], v[156:159], v[240:243], v[72:75]
	v_mfma_f32_16x16x32_bf16 v[124:127], v[144:147], v[194:197], v[124:127]
	v_mfma_f32_16x16x32_bf16 v[120:123], v[160:163], v[194:197], v[120:123]
	v_mfma_f32_16x16x32_bf16 v[108:111], v[144:147], v[202:205], v[108:111]
	v_mfma_f32_16x16x32_bf16 v[104:107], v[160:163], v[202:205], v[104:107]
	v_mfma_f32_16x16x32_bf16 v[92:95], v[144:147], v[236:239], v[92:95]
	v_mfma_f32_16x16x32_bf16 v[88:91], v[160:163], v[236:239], v[88:91]
	v_mfma_f32_16x16x32_bf16 v[76:79], v[144:147], v[244:247], v[76:79]
	v_mfma_f32_16x16x32_bf16 v[72:75], v[160:163], v[244:247], v[72:75]
	s_setprio 0
	s_setprio 1
	v_mfma_f32_16x16x32_bf16 v[116:119], v[164:167], v[190:193], v[116:119]
	v_mfma_f32_16x16x32_bf16 v[112:115], v[182:185], v[190:193], v[112:115]
	v_mfma_f32_16x16x32_bf16 v[100:103], v[164:167], v[198:201], v[100:103]
	v_mfma_f32_16x16x32_bf16 v[96:99], v[182:185], v[198:201], v[96:99]
	v_mfma_f32_16x16x32_bf16 v[84:87], v[164:167], v[228:231], v[84:87]
	v_mfma_f32_16x16x32_bf16 v[80:83], v[182:185], v[228:231], v[80:83]
	v_mfma_f32_16x16x32_bf16 v[68:71], v[164:167], v[240:243], v[68:71]
	v_mfma_f32_16x16x32_bf16 v[64:67], v[182:185], v[240:243], v[64:67]
	v_mfma_f32_16x16x32_bf16 v[116:119], v[168:171], v[194:197], v[116:119]
	v_mfma_f32_16x16x32_bf16 v[112:115], v[186:189], v[194:197], v[112:115]
	v_mfma_f32_16x16x32_bf16 v[100:103], v[168:171], v[202:205], v[100:103]
	v_mfma_f32_16x16x32_bf16 v[96:99], v[186:189], v[202:205], v[96:99]
	s_setprio 2
	s_barrier
	v_mfma_f32_16x16x32_bf16 v[84:87], v[168:171], v[236:239], v[84:87]
	v_mfma_f32_16x16x32_bf16 v[80:83], v[186:189], v[236:239], v[80:83]
	v_mfma_f32_16x16x32_bf16 v[68:71], v[168:171], v[244:247], v[68:71]
	v_mfma_f32_16x16x32_bf16 v[64:67], v[186:189], v[244:247], v[64:67]
	s_setprio 0
	s_add_i32 s39, s39, s26
	v_lshl_add_u64 v[148:149], s[22:23], 0, v[130:131]
	s_mov_b32 m0, s39
	ds_read_b128 v[190:193], v154 offset:16384
	ds_read_b128 v[194:197], v154 offset:17408
	ds_read_b128 v[198:201], v154 offset:18432
	ds_read_b128 v[202:205], v154 offset:19456
	ds_read_b128 v[228:231], v154 offset:20480
	ds_read_b128 v[236:239], v154 offset:21504
	ds_read_b128 v[240:243], v154 offset:22528
	ds_read_b128 v[244:247], v154 offset:23552
	global_load_lds_dwordx4 v[148:149], off
	s_add_i32 m0, s39, 0x2000
	s_add_u32 s52, s22, 0x40000
	v_lshl_add_u64 v[206:207], s[22:23], 0, v[134:135]
	s_addc_u32 s53, s23, 0
	s_add_i32 s39, s45, s26
	global_load_lds_dwordx4 v[206:207], off
	v_lshl_add_u64 v[248:249], s[52:53], 0, v[130:131]
	s_mov_b32 m0, s39
	v_lshl_add_u64 v[250:251], s[24:25], 0, v[132:133]
	global_load_lds_dwordx4 v[248:249], off
	v_lshl_add_u64 v[248:249], s[52:53], 0, v[134:135]
	s_add_i32 m0, s39, 0x2000
	s_nop 0
	global_load_lds_dwordx4 v[248:249], off
	s_waitcnt vmcnt(6)
	s_waitcnt lgkmcnt(0)
	s_barrier
; #define PG8_STAGE(bufoff, gbase, voff) do { _Pragma("unroll") for (int _i = 0; _i < 2; ++_i) \
;         __builtin_amdgcn_global_load_lds((const unsigned*)((const char*)(gbase) + (voff)[_i]), (PG8_LAS unsigned*)(lds + (bufoff) + ldsw + _i * 8192), 16, 0, 0); } while (0)
; #define PG8_LDA(dst, b, h) do { _Pragma("unroll") for (int m = 0; m < 4; ++m) _Pragma("unroll") for (int k = 0; k < 2; ++k) dst[m][k] = *(const PG8_LAS bf16x8*)(lds + PG8_SA(b, h) + aoff + m * 2048 + k * 1024); } while (0)
; #define PG8_LDB(dst, b, h) do { _Pragma("unroll") for (int n = 0; n < 2; ++n) _Pragma("unroll") for (int k = 0; k < 2; ++k) dst[n][k] = *(const PG8_LAS bf16x8*)(lds + PG8_SB(b, h) + boff + n * 2048 + k * 1024); } while (0)
; #define PG8_MMA(ai, bj, At, Bt) do { __builtin_amdgcn_s_setprio(1); _Pragma("unroll") for (int m = 0; m < 4; ++m) _Pragma("unroll") for (int n = 0; n < 2; ++n) _Pragma("unroll") for (int k = 0; k < 2; ++k) \
;         acc[ai][bj][m][n] = __builtin_amdgcn_mfma_f32_16x16x32_bf16(Bt[n][k], At[m][k], acc[ai][bj][m][n], 0, 0, 0); __builtin_amdgcn_s_setprio(0); } while (0)
; #define PG8_WAIT_V(n) asm volatile("s_waitcnt vmcnt(" #n ")" ::: "memory")
; #define PG8_WAIT_L(n) asm volatile("s_waitcnt lgkmcnt(" #n ")" ::: "memory")
; #define PG8_BAR __builtin_amdgcn_s_barrier()
; #define PG8_SCHED __builtin_amdgcn_sched_barrier(0)
; template <class Epi, class Sched, bool ALIGN_EPI = false, bool SP2 = false>
; __device__ __forceinline__ void gemm_phase(PG8_LAS unsigned char* lds, const Gemm g, const Sched& S, const Epi& E) {
;     ...
;             PG8_WAIT_V(8); PG8_WAIT_L(0); PG8_BAR; PG8_MMA(1, 0, At, B0); PG8_MMA(1, 1, At, B1); PG8_BAR; PG8_SCHED;
;             PG8_LDB(B0, 1, 0); PG8_LDB(B1, 1, 1); PG8_SCHED; PG8_LDA(At, 1, 0); PG8_STAGE(PG8_SA(0, 1), a2 + hstep, voffA);
;             PG8_WAIT_V(8); PG8_WAIT_L(0); PG8_BAR; PG8_MMA(0, 0, At, B0); PG8_MMA(0, 1, At, B1); PG8_BAR; PG8_SCHED;
	s_setprio 1
	s_waitcnt lgkmcnt(0)
	v_mfma_f32_16x16x32_bf16 v[60:63], v[140:143], v[190:193], v[60:63]
	v_mfma_f32_16x16x32_bf16 v[56:59], v[156:159], v[190:193], v[56:59]
	v_mfma_f32_16x16x32_bf16 v[44:47], v[140:143], v[198:201], v[44:47]
	v_mfma_f32_16x16x32_bf16 v[40:43], v[156:159], v[198:201], v[40:43]
	v_lshl_add_u64 v[248:249], s[24:25], 0, v[128:129]
	s_mov_b32 m0, s19
	s_nop 0
	global_load_lds_dwordx4 v[248:249], off
	v_mfma_f32_16x16x32_bf16 v[28:31], v[140:143], v[228:231], v[28:31]
	v_mfma_f32_16x16x32_bf16 v[24:27], v[156:159], v[228:231], v[24:27]
	v_mfma_f32_16x16x32_bf16 v[12:15], v[140:143], v[240:243], v[12:15]
	v_mfma_f32_16x16x32_bf16 v[8:11], v[156:159], v[240:243], v[8:11]
	v_mfma_f32_16x16x32_bf16 v[60:63], v[144:147], v[194:197], v[60:63]
	v_mfma_f32_16x16x32_bf16 v[56:59], v[160:163], v[194:197], v[56:59]
	s_mov_b32 m0, s27
	s_nop 0
	global_load_lds_dwordx4 v[250:251], off
	v_mfma_f32_16x16x32_bf16 v[44:47], v[144:147], v[202:205], v[44:47]
	v_mfma_f32_16x16x32_bf16 v[40:43], v[160:163], v[202:205], v[40:43]
	v_mfma_f32_16x16x32_bf16 v[28:31], v[144:147], v[236:239], v[28:31]
	v_mfma_f32_16x16x32_bf16 v[24:27], v[160:163], v[236:239], v[24:27]
	v_mfma_f32_16x16x32_bf16 v[12:15], v[144:147], v[244:247], v[12:15]
	v_mfma_f32_16x16x32_bf16 v[8:11], v[160:163], v[244:247], v[8:11]
	s_setprio 0
	s_setprio 1
	v_mfma_f32_16x16x32_bf16 v[52:55], v[164:167], v[190:193], v[52:55]
	v_mfma_f32_16x16x32_bf16 v[48:51], v[182:185], v[190:193], v[48:51]
	v_mfma_f32_16x16x32_bf16 v[36:39], v[164:167], v[198:201], v[36:39]
	v_mfma_f32_16x16x32_bf16 v[32:35], v[182:185], v[198:201], v[32:35]
	v_mfma_f32_16x16x32_bf16 v[20:23], v[164:167], v[228:231], v[20:23]
	v_mfma_f32_16x16x32_bf16 v[16:19], v[182:185], v[228:231], v[16:19]
	v_mfma_f32_16x16x32_bf16 v[4:7], v[164:167], v[240:243], v[4:7]
	v_mfma_f32_16x16x32_bf16 v[0:3], v[182:185], v[240:243], v[0:3]
	v_mfma_f32_16x16x32_bf16 v[52:55], v[168:171], v[194:197], v[52:55]
	v_mfma_f32_16x16x32_bf16 v[48:51], v[186:189], v[194:197], v[48:51]
	v_mfma_f32_16x16x32_bf16 v[36:39], v[168:171], v[202:205], v[36:39]
	v_mfma_f32_16x16x32_bf16 v[32:35], v[186:189], v[202:205], v[32:35]
	s_setprio 2
	s_barrier
	v_mfma_f32_16x16x32_bf16 v[20:23], v[168:171], v[236:239], v[20:23]
	v_mfma_f32_16x16x32_bf16 v[16:19], v[186:189], v[236:239], v[16:19]
	v_mfma_f32_16x16x32_bf16 v[4:7], v[168:171], v[244:247], v[4:7]
	v_mfma_f32_16x16x32_bf16 v[0:3], v[186:189], v[244:247], v[0:3]
	s_setprio 0
	s_add_i32 s39, 0, 0x18000
	v_add_u32_e32 v155, s39, v151
	s_add_i32 s45, 0, 0x1c000
	ds_read_b128 v[140:143], v155
	ds_read_b128 v[144:147], v155 offset:1024
	ds_read_b128 v[156:159], v155 offset:2048
	ds_read_b128 v[160:163], v155 offset:3072
	v_add_u32_e32 v155, s45, v151
	ds_read_b128 v[164:167], v155
	ds_read_b128 v[168:171], v155 offset:1024
	ds_read_b128 v[182:185], v155 offset:2048
	ds_read_b128 v[186:189], v155 offset:3072
	s_add_u32 s24, s24, 0x40000
	s_addc_u32 s25, s25, 0
	s_mov_b32 m0, s28
	v_lshl_add_u64 v[210:211], s[24:25], 0, v[128:129]
	ds_read_b128 v[190:193], v154 offset:32768
	ds_read_b128 v[194:197], v154 offset:33792
	ds_read_b128 v[198:201], v154 offset:34816
	ds_read_b128 v[202:205], v154 offset:35840
	ds_read_b128 v[228:231], v154 offset:36864
	ds_read_b128 v[236:239], v154 offset:37888
	ds_read_b128 v[240:243], v154 offset:38912
	ds_read_b128 v[244:247], v154 offset:39936
	global_load_lds_dwordx4 v[210:211], off
	v_lshl_add_u64 v[210:211], s[24:25], 0, v[132:133]
	s_mov_b32 m0, s29
	s_nop 0
	global_load_lds_dwordx4 v[210:211], off
	s_waitcnt vmcnt(8)
	s_waitcnt lgkmcnt(0)
	s_barrier
	s_setprio 1
	s_waitcnt lgkmcnt(0)
	v_mfma_f32_16x16x32_bf16 v[124:127], v[140:143], v[190:193], v[124:127]
	v_mfma_f32_16x16x32_bf16 v[120:123], v[156:159], v[190:193], v[120:123]
	v_mfma_f32_16x16x32_bf16 v[108:111], v[140:143], v[198:201], v[108:111]
	v_mfma_f32_16x16x32_bf16 v[104:107], v[156:159], v[198:201], v[104:107]
	v_mfma_f32_16x16x32_bf16 v[92:95], v[140:143], v[228:231], v[92:95]
	v_mfma_f32_16x16x32_bf16 v[88:91], v[156:159], v[228:231], v[88:91]
	v_mfma_f32_16x16x32_bf16 v[76:79], v[140:143], v[240:243], v[76:79]
	v_mfma_f32_16x16x32_bf16 v[72:75], v[156:159], v[240:243], v[72:75]
	v_mfma_f32_16x16x32_bf16 v[124:127], v[144:147], v[194:197], v[124:127]
	v_mfma_f32_16x16x32_bf16 v[120:123], v[160:163], v[194:197], v[120:123]
	v_mfma_f32_16x16x32_bf16 v[108:111], v[144:147], v[202:205], v[108:111]
	v_mfma_f32_16x16x32_bf16 v[104:107], v[160:163], v[202:205], v[104:107]
	v_mfma_f32_16x16x32_bf16 v[92:95], v[144:147], v[236:239], v[92:95]
	v_mfma_f32_16x16x32_bf16 v[88:91], v[160:163], v[236:239], v[88:91]
	v_mfma_f32_16x16x32_bf16 v[76:79], v[144:147], v[244:247], v[76:79]
	v_mfma_f32_16x16x32_bf16 v[72:75], v[160:163], v[244:247], v[72:75]
	s_setprio 0
	s_setprio 1
	v_mfma_f32_16x16x32_bf16 v[116:119], v[164:167], v[190:193], v[116:119]
	v_mfma_f32_16x16x32_bf16 v[112:115], v[182:185], v[190:193], v[112:115]
	v_mfma_f32_16x16x32_bf16 v[100:103], v[164:167], v[198:201], v[100:103]
	v_mfma_f32_16x16x32_bf16 v[96:99], v[182:185], v[198:201], v[96:99]
	v_mfma_f32_16x16x32_bf16 v[84:87], v[164:167], v[228:231], v[84:87]
	v_mfma_f32_16x16x32_bf16 v[80:83], v[182:185], v[228:231], v[80:83]
	v_mfma_f32_16x16x32_bf16 v[68:71], v[164:167], v[240:243], v[68:71]
	v_mfma_f32_16x16x32_bf16 v[64:67], v[182:185], v[240:243], v[64:67]
	v_mfma_f32_16x16x32_bf16 v[116:119], v[168:171], v[194:197], v[116:119]
	v_mfma_f32_16x16x32_bf16 v[112:115], v[186:189], v[194:197], v[112:115]
	v_mfma_f32_16x16x32_bf16 v[100:103], v[168:171], v[202:205], v[100:103]
	v_mfma_f32_16x16x32_bf16 v[96:99], v[186:189], v[202:205], v[96:99]
	s_setprio 2
	s_barrier
; #define PG8_STAGE(bufoff, gbase, voff) do { _Pragma("unroll") for (int _i = 0; _i < 2; ++_i) \
;         __builtin_amdgcn_global_load_lds((const unsigned*)((const char*)(gbase) + (voff)[_i]), (PG8_LAS unsigned*)(lds + (bufoff) + ldsw + _i * 8192), 16, 0, 0); } while (0)
; #define PG8_LDA(dst, b, h) do { _Pragma("unroll") for (int m = 0; m < 4; ++m) _Pragma("unroll") for (int k = 0; k < 2; ++k) dst[m][k] = *(const PG8_LAS bf16x8*)(lds + PG8_SA(b, h) + aoff + m * 2048 + k * 1024); } while (0)
; #define PG8_MMA(ai, bj, At, Bt) do { __builtin_amdgcn_s_setprio(1); _Pragma("unroll") for (int m = 0; m < 4; ++m) _Pragma("unroll") for (int n = 0; n < 2; ++n) _Pragma("unroll") for (int k = 0; k < 2; ++k) \
;         acc[ai][bj][m][n] = __builtin_amdgcn_mfma_f32_16x16x32_bf16(Bt[n][k], At[m][k], acc[ai][bj][m][n], 0, 0, 0); __builtin_amdgcn_s_setprio(0); } while (0)
; #define PG8_WAIT_V(n) asm volatile("s_waitcnt vmcnt(" #n ")" ::: "memory")
; #define PG8_WAIT_L(n) asm volatile("s_waitcnt lgkmcnt(" #n ")" ::: "memory")
; #define PG8_BAR __builtin_amdgcn_s_barrier()
; #define PG8_SCHED __builtin_amdgcn_sched_barrier(0)
; template <class Epi, class Sched, bool ALIGN_EPI = false, bool SP2 = false>
; __device__ __forceinline__ void gemm_phase(PG8_LAS unsigned char* lds, const Gemm g, const Sched& S, const Epi& E) {
;     ...
;             PG8_LDA(At, 1, 1); PG8_STAGE(PG8_SB(1, 0), b3, voffB); PG8_STAGE(PG8_SB(1, 1), b3 + hstep, voffB); PG8_STAGE(PG8_SA(1, 0), a3, voffA);
;             PG8_WAIT_V(8); PG8_WAIT_L(0); PG8_BAR; PG8_MMA(1, 0, At, B0); PG8_MMA(1, 1, At, B1); PG8_BAR; PG8_SCHED;
	v_mfma_f32_16x16x32_bf16 v[84:87], v[168:171], v[236:239], v[84:87]
	v_mfma_f32_16x16x32_bf16 v[80:83], v[186:189], v[236:239], v[80:83]
	v_mfma_f32_16x16x32_bf16 v[68:71], v[168:171], v[244:247], v[68:71]
	v_mfma_f32_16x16x32_bf16 v[64:67], v[186:189], v[244:247], v[64:67]
	s_setprio 0
	s_add_i32 s24, s39, s26
	v_lshl_add_u64 v[148:149], v[148:149], 0, s[88:89]
	s_mov_b32 m0, s24
	ds_read_b128 v[190:193], v154 offset:49152
	ds_read_b128 v[194:197], v154 offset:50176
	ds_read_b128 v[198:201], v154 offset:51200
	ds_read_b128 v[202:205], v154 offset:52224
	ds_read_b128 v[228:231], v154 offset:53248
	ds_read_b128 v[236:239], v154 offset:54272
	ds_read_b128 v[240:243], v154 offset:55296
	ds_read_b128 v[244:247], v154 offset:56320
	global_load_lds_dwordx4 v[148:149], off
	s_add_i32 m0, s24, 0x2000
	s_add_u32 s22, s22, 0x40080
	v_lshl_add_u64 v[148:149], v[206:207], 0, s[88:89]
	s_addc_u32 s23, s23, 0
	s_add_i32 s24, s45, s26
	global_load_lds_dwordx4 v[148:149], off
	v_lshl_add_u64 v[148:149], s[22:23], 0, v[130:131]
	s_mov_b32 m0, s24
	s_nop 0
	global_load_lds_dwordx4 v[148:149], off
	v_lshl_add_u64 v[148:149], s[22:23], 0, v[134:135]
	s_add_i32 m0, s24, 0x2000
	s_nop 0
	global_load_lds_dwordx4 v[148:149], off
	s_waitcnt vmcnt(6)
	s_waitcnt lgkmcnt(0)
	s_barrier
	s_setprio 1
	s_waitcnt lgkmcnt(0)
	v_mfma_f32_16x16x32_bf16 v[60:63], v[140:143], v[190:193], v[60:63]
	v_mfma_f32_16x16x32_bf16 v[56:59], v[156:159], v[190:193], v[56:59]
	v_mfma_f32_16x16x32_bf16 v[44:47], v[140:143], v[198:201], v[44:47]
	v_mfma_f32_16x16x32_bf16 v[40:43], v[156:159], v[198:201], v[40:43]
	v_lshl_add_u64 v[148:149], v[248:249], 0, s[88:89]
	s_mov_b32 m0, s30
	s_nop 0
	global_load_lds_dwordx4 v[148:149], off
	v_mfma_f32_16x16x32_bf16 v[28:31], v[140:143], v[228:231], v[28:31]
	v_mfma_f32_16x16x32_bf16 v[24:27], v[156:159], v[228:231], v[24:27]
	v_mfma_f32_16x16x32_bf16 v[12:15], v[140:143], v[240:243], v[12:15]
	v_mfma_f32_16x16x32_bf16 v[8:11], v[156:159], v[240:243], v[8:11]
	v_mfma_f32_16x16x32_bf16 v[60:63], v[144:147], v[194:197], v[60:63]
	v_mfma_f32_16x16x32_bf16 v[56:59], v[160:163], v[194:197], v[56:59]
	v_lshl_add_u64 v[148:149], v[250:251], 0, s[88:89]
	s_mov_b32 m0, s31
	s_nop 0
	global_load_lds_dwordx4 v[148:149], off
	v_mfma_f32_16x16x32_bf16 v[44:47], v[144:147], v[202:205], v[44:47]
	v_mfma_f32_16x16x32_bf16 v[40:43], v[160:163], v[202:205], v[40:43]
	v_mfma_f32_16x16x32_bf16 v[28:31], v[144:147], v[236:239], v[28:31]
	v_mfma_f32_16x16x32_bf16 v[24:27], v[160:163], v[236:239], v[24:27]
	v_mfma_f32_16x16x32_bf16 v[12:15], v[144:147], v[244:247], v[12:15]
	v_mfma_f32_16x16x32_bf16 v[8:11], v[160:163], v[244:247], v[8:11]
	s_setprio 0
	s_setprio 1
	v_mfma_f32_16x16x32_bf16 v[52:55], v[164:167], v[190:193], v[52:55]
	v_mfma_f32_16x16x32_bf16 v[48:51], v[182:185], v[190:193], v[48:51]
	v_mfma_f32_16x16x32_bf16 v[36:39], v[164:167], v[198:201], v[36:39]
	v_mfma_f32_16x16x32_bf16 v[32:35], v[182:185], v[198:201], v[32:35]
	v_mfma_f32_16x16x32_bf16 v[20:23], v[164:167], v[228:231], v[20:23]
	v_mfma_f32_16x16x32_bf16 v[16:19], v[182:185], v[228:231], v[16:19]
	v_mfma_f32_16x16x32_bf16 v[4:7], v[164:167], v[240:243], v[4:7]
	v_mfma_f32_16x16x32_bf16 v[0:3], v[182:185], v[240:243], v[0:3]
	v_mfma_f32_16x16x32_bf16 v[52:55], v[168:171], v[194:197], v[52:55]
	v_mfma_f32_16x16x32_bf16 v[48:51], v[186:189], v[194:197], v[48:51]
	v_mfma_f32_16x16x32_bf16 v[36:39], v[168:171], v[202:205], v[36:39]
	v_mfma_f32_16x16x32_bf16 v[32:35], v[186:189], v[202:205], v[32:35]
	s_setprio 2
	s_barrier
	v_mfma_f32_16x16x32_bf16 v[20:23], v[168:171], v[236:239], v[20:23]
	v_mfma_f32_16x16x32_bf16 v[16:19], v[186:189], v[236:239], v[16:19]
	v_mfma_f32_16x16x32_bf16 v[4:7], v[168:171], v[244:247], v[4:7]
	v_mfma_f32_16x16x32_bf16 v[0:3], v[186:189], v[244:247], v[0:3]
	s_setprio 0
	s_add_i32 s38, s38, 2
	s_add_u32 s20, s20, 0x100
	s_addc_u32 s21, s21, 0
	s_add_u32 s36, s36, 0x100
	s_addc_u32 s37, s37, 0
	s_cmp_gt_u32 s38, 13
	s_cbranch_scc0 .LBB0_274
	s_and_b64 vcc, exec, s[8:9]
	s_cbranch_vccz .LBB0_295
	s_barrier
	v_lshl_add_u32 v155, s4, 8, v150
	s_cmp_gt_i32 s18, 7
	s_mov_b64 s[4:5], -1
	s_cbranch_scc1 .LBB0_296

; #define PG8_STAGE(bufoff, gbase, voff) do { _Pragma("unroll") for (int _i = 0; _i < 2; ++_i) \
;         __builtin_amdgcn_global_load_lds((const unsigned*)((const char*)(gbase) + (voff)[_i]), (PG8_LAS unsigned*)(lds + (bufoff) + ldsw + _i * 8192), 16, 0, 0); } while (0)
; #define PG8_LDA(dst, b, h) do { _Pragma("unroll") for (int m = 0; m < 4; ++m) _Pragma("unroll") for (int k = 0; k < 2; ++k) dst[m][k] = *(const PG8_LAS bf16x8*)(lds + PG8_SA(b, h) + aoff + m * 2048 + k * 1024); } while (0)
; #define PG8_LDB(dst, b, h) do { _Pragma("unroll") for (int n = 0; n < 2; ++n) _Pragma("unroll") for (int k = 0; k < 2; ++k) dst[n][k] = *(const PG8_LAS bf16x8*)(lds + PG8_SB(b, h) + boff + n * 2048 + k * 1024); } while (0)
; #define PG8_MMA(ai, bj, At, Bt) do { __builtin_amdgcn_s_setprio(1); _Pragma("unroll") for (int m = 0; m < 4; ++m) _Pragma("unroll") for (int n = 0; n < 2; ++n) _Pragma("unroll") for (int k = 0; k < 2; ++k) \
;         acc[ai][bj][m][n] = __builtin_amdgcn_mfma_f32_16x16x32_bf16(Bt[n][k], At[m][k], acc[ai][bj][m][n], 0, 0, 0); __builtin_amdgcn_s_setprio(0); } while (0)
; #define PG8_WAIT_V(n) asm volatile("s_waitcnt vmcnt(" #n ")" ::: "memory")
; #define PG8_WAIT_L(n) asm volatile("s_waitcnt lgkmcnt(" #n ")" ::: "memory")
; #define PG8_BAR __builtin_amdgcn_s_barrier()
; #define PG8_SCHED __builtin_amdgcn_sched_barrier(0)
; template <class Epi, class Sched, bool ALIGN_EPI = false, bool SP2 = false>
; __device__ __forceinline__ void gemm_phase(PG8_LAS unsigned char* lds, const Gemm g, const Sched& S, const Epi& E) {
;     ...
;             PG8_LDB(B0, 0, 0); PG8_LDB(B1, 0, 1); PG8_SCHED; PG8_LDA(At, 0, 0); PG8_STAGE(PG8_SA(1, 1), a1 + hstep, voffA);
;             PG8_WAIT_V(8); PG8_WAIT_L(0); PG8_BAR; PG8_MMA(0, 0, At, B0); PG8_MMA(0, 1, At, B1); PG8_BAR; PG8_SCHED;
;             PG8_LDA(At, 0, 1); PG8_STAGE(PG8_SB(0, 0), b2, voffB); PG8_STAGE(PG8_SB(0, 1), b2 + hstep, voffB); PG8_STAGE(PG8_SA(0, 0), a2, voffA);
;             PG8_WAIT_V(8); PG8_WAIT_L(0); PG8_BAR; PG8_MMA(1, 0, At, B0); PG8_MMA(1, 1, At, B1); PG8_BAR; PG8_SCHED;
.LBB0_613:
	s_add_u32 s36, s34, 0xfffc0080
	s_addc_u32 s37, s35, -1
	s_add_i32 s68, 0, 0x10000
	s_cmp_eq_u32 s67, 12
	s_cselect_b32 s39, s27, s37
	s_cselect_b32 s38, s63, s36
	s_cselect_b32 s37, s25, s66
	s_cselect_b32 s36, s64, s65
	s_add_i32 s70, 0, 0x14000
	v_add_u32_e32 v84, s68, v228
	v_add_u32_e32 v156, s70, v228
	ds_read_b128 v[68:71], v84
	ds_read_b128 v[72:75], v84 offset:1024
	ds_read_b128 v[80:83], v84 offset:2048
	ds_read_b128 v[84:87], v84 offset:3072
	ds_read_b128 v[144:147], v156
	ds_read_b128 v[148:151], v156 offset:1024
	ds_read_b128 v[152:155], v156 offset:2048
	ds_read_b128 v[156:159], v156 offset:3072
	v_lshl_add_u64 v[210:211], s[34:35], 0, v[188:189]
	s_add_i32 m0, s52, 0xc000
	ds_read_b128 v[160:163], v230
	ds_read_b128 v[164:167], v230 offset:1024
	ds_read_b128 v[168:171], v230 offset:2048
	ds_read_b128 v[192:195], v230 offset:3072
	ds_read_b128 v[196:199], v230 offset:4096
	ds_read_b128 v[200:203], v230 offset:5120
	ds_read_b128 v[204:207], v230 offset:6144
	ds_read_b128 v[236:239], v230 offset:7168
	global_load_lds_dwordx4 v[210:211], off
	v_lshl_add_u64 v[210:211], s[34:35], 0, v[190:191]
	s_add_i32 m0, s52, 0xe000
	s_nop 0
	global_load_lds_dwordx4 v[210:211], off
	s_waitcnt vmcnt(8)
	s_waitcnt lgkmcnt(0)
	s_barrier
	s_setprio 1
	s_waitcnt lgkmcnt(0)
	v_mfma_f32_16x16x32_bf16 v[140:143], v[68:71], v[160:163], v[140:143]
	v_mfma_f32_16x16x32_bf16 v[136:139], v[80:83], v[160:163], v[136:139]
	v_mfma_f32_16x16x32_bf16 v[124:127], v[68:71], v[168:171], v[124:127]
	v_mfma_f32_16x16x32_bf16 v[120:123], v[80:83], v[168:171], v[120:123]
	v_mfma_f32_16x16x32_bf16 v[108:111], v[68:71], v[196:199], v[108:111]
	v_mfma_f32_16x16x32_bf16 v[104:107], v[80:83], v[196:199], v[104:107]
	v_mfma_f32_16x16x32_bf16 v[92:95], v[68:71], v[204:207], v[92:95]
	v_mfma_f32_16x16x32_bf16 v[88:91], v[80:83], v[204:207], v[88:91]
	v_mfma_f32_16x16x32_bf16 v[140:143], v[72:75], v[164:167], v[140:143]
	v_mfma_f32_16x16x32_bf16 v[136:139], v[84:87], v[164:167], v[136:139]
	v_mfma_f32_16x16x32_bf16 v[124:127], v[72:75], v[192:195], v[124:127]
	v_mfma_f32_16x16x32_bf16 v[120:123], v[84:87], v[192:195], v[120:123]
	v_mfma_f32_16x16x32_bf16 v[108:111], v[72:75], v[200:203], v[108:111]
	v_mfma_f32_16x16x32_bf16 v[104:107], v[84:87], v[200:203], v[104:107]
	v_mfma_f32_16x16x32_bf16 v[92:95], v[72:75], v[236:239], v[92:95]
	v_mfma_f32_16x16x32_bf16 v[88:91], v[84:87], v[236:239], v[88:91]
	s_setprio 0
	s_setprio 1
	v_mfma_f32_16x16x32_bf16 v[132:135], v[144:147], v[160:163], v[132:135]
	v_mfma_f32_16x16x32_bf16 v[128:131], v[152:155], v[160:163], v[128:131]
	v_mfma_f32_16x16x32_bf16 v[116:119], v[144:147], v[168:171], v[116:119]
	v_mfma_f32_16x16x32_bf16 v[112:115], v[152:155], v[168:171], v[112:115]
	v_mfma_f32_16x16x32_bf16 v[100:103], v[144:147], v[196:199], v[100:103]
	v_mfma_f32_16x16x32_bf16 v[96:99], v[152:155], v[196:199], v[96:99]
	v_mfma_f32_16x16x32_bf16 v[76:79], v[144:147], v[204:207], v[76:79]
	v_mfma_f32_16x16x32_bf16 v[64:67], v[152:155], v[204:207], v[64:67]
	v_mfma_f32_16x16x32_bf16 v[132:135], v[148:151], v[164:167], v[132:135]
	v_mfma_f32_16x16x32_bf16 v[128:131], v[156:159], v[164:167], v[128:131]
	v_mfma_f32_16x16x32_bf16 v[116:119], v[148:151], v[192:195], v[116:119]
	v_mfma_f32_16x16x32_bf16 v[112:115], v[156:159], v[192:195], v[112:115]
	s_setprio 2
	s_barrier
	v_mfma_f32_16x16x32_bf16 v[100:103], v[148:151], v[200:203], v[100:103]
	v_mfma_f32_16x16x32_bf16 v[96:99], v[156:159], v[200:203], v[96:99]
	v_mfma_f32_16x16x32_bf16 v[76:79], v[148:151], v[236:239], v[76:79]
	v_mfma_f32_16x16x32_bf16 v[64:67], v[156:159], v[236:239], v[64:67]
	s_setprio 0
	s_add_i32 s68, s68, s45
	v_lshl_add_u64 v[210:211], s[36:37], 0, v[172:173]
	s_mov_b32 m0, s68
	ds_read_b128 v[160:163], v230 offset:16384
	ds_read_b128 v[164:167], v230 offset:17408
	ds_read_b128 v[168:171], v230 offset:18432
	ds_read_b128 v[192:195], v230 offset:19456
	ds_read_b128 v[196:199], v230 offset:20480
	ds_read_b128 v[200:203], v230 offset:21504
	ds_read_b128 v[204:207], v230 offset:22528
	ds_read_b128 v[236:239], v230 offset:23552
	global_load_lds_dwordx4 v[210:211], off
	s_add_i32 m0, s68, 0x2000
	s_add_u32 s68, s36, 0x40000
	v_lshl_add_u64 v[240:241], s[36:37], 0, v[182:183]
	s_addc_u32 s69, s37, 0
	s_add_i32 s70, s70, s45
	global_load_lds_dwordx4 v[240:241], off
	v_lshl_add_u64 v[242:243], s[68:69], 0, v[172:173]
	s_mov_b32 m0, s70
	v_lshl_add_u64 v[244:245], s[38:39], 0, v[184:185]
	global_load_lds_dwordx4 v[242:243], off
	v_lshl_add_u64 v[242:243], s[68:69], 0, v[182:183]
	s_add_i32 m0, s70, 0x2000
	s_nop 0
	global_load_lds_dwordx4 v[242:243], off
	s_waitcnt vmcnt(6)
	s_waitcnt lgkmcnt(0)
	s_barrier
; #define PG8_STAGE(bufoff, gbase, voff) do { _Pragma("unroll") for (int _i = 0; _i < 2; ++_i) \
;         __builtin_amdgcn_global_load_lds((const unsigned*)((const char*)(gbase) + (voff)[_i]), (PG8_LAS unsigned*)(lds + (bufoff) + ldsw + _i * 8192), 16, 0, 0); } while (0)
; #define PG8_LDA(dst, b, h) do { _Pragma("unroll") for (int m = 0; m < 4; ++m) _Pragma("unroll") for (int k = 0; k < 2; ++k) dst[m][k] = *(const PG8_LAS bf16x8*)(lds + PG8_SA(b, h) + aoff + m * 2048 + k * 1024); } while (0)
; #define PG8_LDB(dst, b, h) do { _Pragma("unroll") for (int n = 0; n < 2; ++n) _Pragma("unroll") for (int k = 0; k < 2; ++k) dst[n][k] = *(const PG8_LAS bf16x8*)(lds + PG8_SB(b, h) + boff + n * 2048 + k * 1024); } while (0)
; #define PG8_MMA(ai, bj, At, Bt) do { __builtin_amdgcn_s_setprio(1); _Pragma("unroll") for (int m = 0; m < 4; ++m) _Pragma("unroll") for (int n = 0; n < 2; ++n) _Pragma("unroll") for (int k = 0; k < 2; ++k) \
;         acc[ai][bj][m][n] = __builtin_amdgcn_mfma_f32_16x16x32_bf16(Bt[n][k], At[m][k], acc[ai][bj][m][n], 0, 0, 0); __builtin_amdgcn_s_setprio(0); } while (0)
; #define PG8_WAIT_V(n) asm volatile("s_waitcnt vmcnt(" #n ")" ::: "memory")
; #define PG8_WAIT_L(n) asm volatile("s_waitcnt lgkmcnt(" #n ")" ::: "memory")
; #define PG8_BAR __builtin_amdgcn_s_barrier()
; #define PG8_SCHED __builtin_amdgcn_sched_barrier(0)
; template <class Epi, class Sched, bool ALIGN_EPI = false, bool SP2 = false>
; __device__ __forceinline__ void gemm_phase(PG8_LAS unsigned char* lds, const Gemm g, const Sched& S, const Epi& E) {
;     ...
;             PG8_WAIT_V(8); PG8_WAIT_L(0); PG8_BAR; PG8_MMA(1, 0, At, B0); PG8_MMA(1, 1, At, B1); PG8_BAR; PG8_SCHED;
;             PG8_LDB(B0, 1, 0); PG8_LDB(B1, 1, 1); PG8_SCHED; PG8_LDA(At, 1, 0); PG8_STAGE(PG8_SA(0, 1), a2 + hstep, voffA);
;             PG8_WAIT_V(8); PG8_WAIT_L(0); PG8_BAR; PG8_MMA(0, 0, At, B0); PG8_MMA(0, 1, At, B1); PG8_BAR; PG8_SCHED;
	s_setprio 1
	s_waitcnt lgkmcnt(0)
	v_mfma_f32_16x16x32_bf16 v[60:63], v[68:71], v[160:163], v[60:63]
	v_mfma_f32_16x16x32_bf16 v[56:59], v[80:83], v[160:163], v[56:59]
	v_mfma_f32_16x16x32_bf16 v[44:47], v[68:71], v[168:171], v[44:47]
	v_mfma_f32_16x16x32_bf16 v[40:43], v[80:83], v[168:171], v[40:43]
	v_lshl_add_u64 v[242:243], s[38:39], 0, v[186:187]
	s_mov_b32 m0, s52
	s_nop 0
	global_load_lds_dwordx4 v[242:243], off
	v_mfma_f32_16x16x32_bf16 v[28:31], v[68:71], v[196:199], v[28:31]
	v_mfma_f32_16x16x32_bf16 v[24:27], v[80:83], v[196:199], v[24:27]
	v_mfma_f32_16x16x32_bf16 v[12:15], v[68:71], v[204:207], v[12:15]
	v_mfma_f32_16x16x32_bf16 v[8:11], v[80:83], v[204:207], v[8:11]
	v_mfma_f32_16x16x32_bf16 v[60:63], v[72:75], v[164:167], v[60:63]
	v_mfma_f32_16x16x32_bf16 v[56:59], v[84:87], v[164:167], v[56:59]
	s_mov_b32 m0, s53
	s_nop 0
	global_load_lds_dwordx4 v[244:245], off
	v_mfma_f32_16x16x32_bf16 v[44:47], v[72:75], v[192:195], v[44:47]
	v_mfma_f32_16x16x32_bf16 v[40:43], v[84:87], v[192:195], v[40:43]
	v_mfma_f32_16x16x32_bf16 v[28:31], v[72:75], v[200:203], v[28:31]
	v_mfma_f32_16x16x32_bf16 v[24:27], v[84:87], v[200:203], v[24:27]
	v_mfma_f32_16x16x32_bf16 v[12:15], v[72:75], v[236:239], v[12:15]
	v_mfma_f32_16x16x32_bf16 v[8:11], v[84:87], v[236:239], v[8:11]
	s_setprio 0
	s_setprio 1
	v_mfma_f32_16x16x32_bf16 v[52:55], v[144:147], v[160:163], v[52:55]
	v_mfma_f32_16x16x32_bf16 v[48:51], v[152:155], v[160:163], v[48:51]
	v_mfma_f32_16x16x32_bf16 v[36:39], v[144:147], v[168:171], v[36:39]
	v_mfma_f32_16x16x32_bf16 v[32:35], v[152:155], v[168:171], v[32:35]
	v_mfma_f32_16x16x32_bf16 v[20:23], v[144:147], v[196:199], v[20:23]
	v_mfma_f32_16x16x32_bf16 v[16:19], v[152:155], v[196:199], v[16:19]
	v_mfma_f32_16x16x32_bf16 v[4:7], v[144:147], v[204:207], v[4:7]
	v_mfma_f32_16x16x32_bf16 v[0:3], v[152:155], v[204:207], v[0:3]
	v_mfma_f32_16x16x32_bf16 v[52:55], v[148:151], v[164:167], v[52:55]
	v_mfma_f32_16x16x32_bf16 v[48:51], v[156:159], v[164:167], v[48:51]
	v_mfma_f32_16x16x32_bf16 v[36:39], v[148:151], v[192:195], v[36:39]
	v_mfma_f32_16x16x32_bf16 v[32:35], v[156:159], v[192:195], v[32:35]
	s_setprio 2
	s_barrier
	v_mfma_f32_16x16x32_bf16 v[20:23], v[148:151], v[200:203], v[20:23]
	v_mfma_f32_16x16x32_bf16 v[16:19], v[156:159], v[200:203], v[16:19]
	v_mfma_f32_16x16x32_bf16 v[4:7], v[148:151], v[236:239], v[4:7]
	v_mfma_f32_16x16x32_bf16 v[0:3], v[156:159], v[236:239], v[0:3]
	s_setprio 0
	s_add_i32 s68, 0, 0x18000
	s_add_i32 s69, 0, 0x1c000
	v_add_u32_e32 v84, s68, v228
	v_add_u32_e32 v156, s69, v228
	ds_read_b128 v[68:71], v84
	ds_read_b128 v[72:75], v84 offset:1024
	ds_read_b128 v[80:83], v84 offset:2048
	ds_read_b128 v[84:87], v84 offset:3072
	ds_read_b128 v[144:147], v156
	ds_read_b128 v[148:151], v156 offset:1024
	ds_read_b128 v[152:155], v156 offset:2048
	ds_read_b128 v[156:159], v156 offset:3072
	s_add_u32 s38, s38, 0x40000
	s_addc_u32 s39, s39, 0
	s_mov_b32 m0, s54
	v_lshl_add_u64 v[246:247], s[38:39], 0, v[186:187]
	ds_read_b128 v[160:163], v230 offset:32768
	ds_read_b128 v[164:167], v230 offset:33792
	ds_read_b128 v[168:171], v230 offset:34816
	ds_read_b128 v[192:195], v230 offset:35840
	ds_read_b128 v[196:199], v230 offset:36864
	ds_read_b128 v[200:203], v230 offset:37888
	ds_read_b128 v[204:207], v230 offset:38912
	ds_read_b128 v[236:239], v230 offset:39936
	global_load_lds_dwordx4 v[246:247], off
	v_lshl_add_u64 v[246:247], s[38:39], 0, v[184:185]
	s_mov_b32 m0, s55
	s_nop 0
	global_load_lds_dwordx4 v[246:247], off
	s_waitcnt vmcnt(8)
	s_waitcnt lgkmcnt(0)
	s_barrier
	s_setprio 1
	s_waitcnt lgkmcnt(0)
	v_mfma_f32_16x16x32_bf16 v[140:143], v[68:71], v[160:163], v[140:143]
	v_mfma_f32_16x16x32_bf16 v[136:139], v[80:83], v[160:163], v[136:139]
	v_mfma_f32_16x16x32_bf16 v[124:127], v[68:71], v[168:171], v[124:127]
	v_mfma_f32_16x16x32_bf16 v[120:123], v[80:83], v[168:171], v[120:123]
	v_mfma_f32_16x16x32_bf16 v[108:111], v[68:71], v[196:199], v[108:111]
	v_mfma_f32_16x16x32_bf16 v[104:107], v[80:83], v[196:199], v[104:107]
	v_mfma_f32_16x16x32_bf16 v[92:95], v[68:71], v[204:207], v[92:95]
	v_mfma_f32_16x16x32_bf16 v[88:91], v[80:83], v[204:207], v[88:91]
	v_mfma_f32_16x16x32_bf16 v[140:143], v[72:75], v[164:167], v[140:143]
	v_mfma_f32_16x16x32_bf16 v[136:139], v[84:87], v[164:167], v[136:139]
	v_mfma_f32_16x16x32_bf16 v[124:127], v[72:75], v[192:195], v[124:127]
	v_mfma_f32_16x16x32_bf16 v[120:123], v[84:87], v[192:195], v[120:123]
	v_mfma_f32_16x16x32_bf16 v[108:111], v[72:75], v[200:203], v[108:111]
	v_mfma_f32_16x16x32_bf16 v[104:107], v[84:87], v[200:203], v[104:107]
	v_mfma_f32_16x16x32_bf16 v[92:95], v[72:75], v[236:239], v[92:95]
	v_mfma_f32_16x16x32_bf16 v[88:91], v[84:87], v[236:239], v[88:91]
	s_setprio 0
	s_setprio 1
	v_mfma_f32_16x16x32_bf16 v[132:135], v[144:147], v[160:163], v[132:135]
	v_mfma_f32_16x16x32_bf16 v[128:131], v[152:155], v[160:163], v[128:131]
	v_mfma_f32_16x16x32_bf16 v[116:119], v[144:147], v[168:171], v[116:119]
	v_mfma_f32_16x16x32_bf16 v[112:115], v[152:155], v[168:171], v[112:115]
	v_mfma_f32_16x16x32_bf16 v[100:103], v[144:147], v[196:199], v[100:103]
	v_mfma_f32_16x16x32_bf16 v[96:99], v[152:155], v[196:199], v[96:99]
	v_mfma_f32_16x16x32_bf16 v[76:79], v[144:147], v[204:207], v[76:79]
	v_mfma_f32_16x16x32_bf16 v[64:67], v[152:155], v[204:207], v[64:67]
	v_mfma_f32_16x16x32_bf16 v[132:135], v[148:151], v[164:167], v[132:135]
	v_mfma_f32_16x16x32_bf16 v[128:131], v[156:159], v[164:167], v[128:131]
	v_mfma_f32_16x16x32_bf16 v[116:119], v[148:151], v[192:195], v[116:119]
	v_mfma_f32_16x16x32_bf16 v[112:115], v[156:159], v[192:195], v[112:115]
	s_setprio 2
	s_barrier
; #define PG8_STAGE(bufoff, gbase, voff) do { _Pragma("unroll") for (int _i = 0; _i < 2; ++_i) \
;         __builtin_amdgcn_global_load_lds((const unsigned*)((const char*)(gbase) + (voff)[_i]), (PG8_LAS unsigned*)(lds + (bufoff) + ldsw + _i * 8192), 16, 0, 0); } while (0)
; #define PG8_LDA(dst, b, h) do { _Pragma("unroll") for (int m = 0; m < 4; ++m) _Pragma("unroll") for (int k = 0; k < 2; ++k) dst[m][k] = *(const PG8_LAS bf16x8*)(lds + PG8_SA(b, h) + aoff + m * 2048 + k * 1024); } while (0)
; #define PG8_MMA(ai, bj, At, Bt) do { __builtin_amdgcn_s_setprio(1); _Pragma("unroll") for (int m = 0; m < 4; ++m) _Pragma("unroll") for (int n = 0; n < 2; ++n) _Pragma("unroll") for (int k = 0; k < 2; ++k) \
;         acc[ai][bj][m][n] = __builtin_amdgcn_mfma_f32_16x16x32_bf16(Bt[n][k], At[m][k], acc[ai][bj][m][n], 0, 0, 0); __builtin_amdgcn_s_setprio(0); } while (0)
; #define PG8_WAIT_V(n) asm volatile("s_waitcnt vmcnt(" #n ")" ::: "memory")
; #define PG8_WAIT_L(n) asm volatile("s_waitcnt lgkmcnt(" #n ")" ::: "memory")
; #define PG8_BAR __builtin_amdgcn_s_barrier()
; #define PG8_SCHED __builtin_amdgcn_sched_barrier(0)
; template <class Epi, class Sched, bool ALIGN_EPI = false, bool SP2 = false>
; __device__ __forceinline__ void gemm_phase(PG8_LAS unsigned char* lds, const Gemm g, const Sched& S, const Epi& E) {
;     ...
;             PG8_LDA(At, 1, 1); PG8_STAGE(PG8_SB(1, 0), b3, voffB); PG8_STAGE(PG8_SB(1, 1), b3 + hstep, voffB); PG8_STAGE(PG8_SA(1, 0), a3, voffA);
;             PG8_WAIT_V(8); PG8_WAIT_L(0); PG8_BAR; PG8_MMA(1, 0, At, B0); PG8_MMA(1, 1, At, B1); PG8_BAR; PG8_SCHED;
	v_mfma_f32_16x16x32_bf16 v[100:103], v[148:151], v[200:203], v[100:103]
	v_mfma_f32_16x16x32_bf16 v[96:99], v[156:159], v[200:203], v[96:99]
	v_mfma_f32_16x16x32_bf16 v[76:79], v[148:151], v[236:239], v[76:79]
	v_mfma_f32_16x16x32_bf16 v[64:67], v[156:159], v[236:239], v[64:67]
	s_setprio 0
	s_add_i32 s38, s68, s45
	v_lshl_add_u64 v[210:211], v[210:211], 0, s[88:89]
	s_mov_b32 m0, s38
	ds_read_b128 v[160:163], v230 offset:49152
	ds_read_b128 v[164:167], v230 offset:50176
	ds_read_b128 v[168:171], v230 offset:51200
	ds_read_b128 v[192:195], v230 offset:52224
	ds_read_b128 v[196:199], v230 offset:53248
	ds_read_b128 v[200:203], v230 offset:54272
	ds_read_b128 v[204:207], v230 offset:55296
	ds_read_b128 v[236:239], v230 offset:56320
	global_load_lds_dwordx4 v[210:211], off
	s_add_i32 m0, s38, 0x2000
	s_add_u32 s36, s36, 0x40080
	v_lshl_add_u64 v[210:211], v[240:241], 0, s[88:89]
	s_addc_u32 s37, s37, 0
	s_add_i32 s38, s69, s45
	global_load_lds_dwordx4 v[210:211], off
	v_lshl_add_u64 v[210:211], s[36:37], 0, v[172:173]
	s_mov_b32 m0, s38
	s_nop 0
	global_load_lds_dwordx4 v[210:211], off
	v_lshl_add_u64 v[210:211], s[36:37], 0, v[182:183]
	s_add_i32 m0, s38, 0x2000
	s_nop 0
	global_load_lds_dwordx4 v[210:211], off
	s_waitcnt vmcnt(6)
	s_waitcnt lgkmcnt(0)
	s_barrier
	s_setprio 1
	s_waitcnt lgkmcnt(0)
	v_mfma_f32_16x16x32_bf16 v[60:63], v[68:71], v[160:163], v[60:63]
	v_mfma_f32_16x16x32_bf16 v[56:59], v[80:83], v[160:163], v[56:59]
	v_mfma_f32_16x16x32_bf16 v[44:47], v[68:71], v[168:171], v[44:47]
	v_mfma_f32_16x16x32_bf16 v[40:43], v[80:83], v[168:171], v[40:43]
	v_lshl_add_u64 v[210:211], v[242:243], 0, s[88:89]
	s_mov_b32 m0, s56
	s_nop 0
	global_load_lds_dwordx4 v[210:211], off
	v_mfma_f32_16x16x32_bf16 v[28:31], v[68:71], v[196:199], v[28:31]
	v_mfma_f32_16x16x32_bf16 v[24:27], v[80:83], v[196:199], v[24:27]
	v_mfma_f32_16x16x32_bf16 v[12:15], v[68:71], v[204:207], v[12:15]
	v_mfma_f32_16x16x32_bf16 v[8:11], v[80:83], v[204:207], v[8:11]
	v_mfma_f32_16x16x32_bf16 v[60:63], v[72:75], v[164:167], v[60:63]
	v_mfma_f32_16x16x32_bf16 v[56:59], v[84:87], v[164:167], v[56:59]
	v_lshl_add_u64 v[210:211], v[244:245], 0, s[88:89]
	s_mov_b32 m0, s57
	s_nop 0
	global_load_lds_dwordx4 v[210:211], off
	v_mfma_f32_16x16x32_bf16 v[44:47], v[72:75], v[192:195], v[44:47]
	v_mfma_f32_16x16x32_bf16 v[40:43], v[84:87], v[192:195], v[40:43]
	v_mfma_f32_16x16x32_bf16 v[28:31], v[72:75], v[200:203], v[28:31]
	v_mfma_f32_16x16x32_bf16 v[24:27], v[84:87], v[200:203], v[24:27]
	v_mfma_f32_16x16x32_bf16 v[12:15], v[72:75], v[236:239], v[12:15]
	v_mfma_f32_16x16x32_bf16 v[8:11], v[84:87], v[236:239], v[8:11]
	s_setprio 0
	s_setprio 1
	v_mfma_f32_16x16x32_bf16 v[52:55], v[144:147], v[160:163], v[52:55]
	v_mfma_f32_16x16x32_bf16 v[48:51], v[152:155], v[160:163], v[48:51]
	v_mfma_f32_16x16x32_bf16 v[36:39], v[144:147], v[168:171], v[36:39]
	v_mfma_f32_16x16x32_bf16 v[32:35], v[152:155], v[168:171], v[32:35]
	v_mfma_f32_16x16x32_bf16 v[20:23], v[144:147], v[196:199], v[20:23]
	v_mfma_f32_16x16x32_bf16 v[16:19], v[152:155], v[196:199], v[16:19]
	v_mfma_f32_16x16x32_bf16 v[4:7], v[144:147], v[204:207], v[4:7]
	v_mfma_f32_16x16x32_bf16 v[0:3], v[152:155], v[204:207], v[0:3]
	v_mfma_f32_16x16x32_bf16 v[52:55], v[148:151], v[164:167], v[52:55]
	v_mfma_f32_16x16x32_bf16 v[48:51], v[156:159], v[164:167], v[48:51]
	v_mfma_f32_16x16x32_bf16 v[36:39], v[148:151], v[192:195], v[36:39]
	v_mfma_f32_16x16x32_bf16 v[32:35], v[156:159], v[192:195], v[32:35]
	s_setprio 2
	s_barrier
	v_mfma_f32_16x16x32_bf16 v[20:23], v[148:151], v[200:203], v[20:23]
	v_mfma_f32_16x16x32_bf16 v[16:19], v[156:159], v[200:203], v[16:19]
	v_mfma_f32_16x16x32_bf16 v[4:7], v[148:151], v[236:239], v[4:7]
	v_mfma_f32_16x16x32_bf16 v[0:3], v[156:159], v[236:239], v[0:3]
	s_setprio 0
	s_add_i32 s67, s67, 2
	s_add_u32 s34, s34, 0x100
	s_addc_u32 s35, s35, 0
	s_add_u32 s65, s65, 0x100
	s_addc_u32 s66, s66, 0
	s_cmp_gt_u32 s67, 13
	s_cbranch_scc0 .LBB0_613
	s_and_b64 vcc, exec, s[22:23]
	s_cbranch_vccz .LBB0_616
	s_barrier
